# DSA QK^T: MFMAs grouped per accumulator (chains of 7) instead of alternating p0/p1
# speedup vs baseline: 1.0018x; 1.0016x over previous
; #define LAS __attribute__((address_space(3)))
; DEVI int crow(int r, int hi) { return (r & 3) + 8 * (r >> 2) + 4 * hi; }
; DEVI float xlane32(float v) { return __shfl_xor(v, 32); }
; DEVI float max3f(float a, float b, float c) { float r; asm("v_max3_f32 %0, %1, %2, %3" : "=v"(r) : "v"(a), "v"(b), "v"(c)); return r; }
; DEVI void qkt(f32x16& p0, f32x16& p1, LAS const unsigned char* Ks, const bf16x8* qr, int r32, int hi) {
;     p0 = (f32x16){0.f, 0.f, 0.f, 0.f, 0.f, 0.f, 0.f, 0.f, 0.f, 0.f, 0.f, 0.f, 0.f, 0.f, 0.f, 0.f}; p1 = p0;
; #pragma unroll
;     for (int d0 = 0; d0 < 8; ++d0) { const int cb = (d0 * 16 + hi * 8) * 2;
;         const bf16x8 b0 = *(LAS const bf16x8*)(Ks + FA_KSWZ(r32, cb));
;         const bf16x8 b1 = *(LAS const bf16x8*)(Ks + FA_KSWZ(32 + r32, cb));
;         p0 = __builtin_amdgcn_mfma_f32_32x32x16_bf16(b0, qr[d0], p0, 0, 0, 0);
;         p1 = __builtin_amdgcn_mfma_f32_32x32x16_bf16(b1, qr[d0], p1, 0, 0, 0); }
; }
; template <int MODE>
; DEVI void attn_unit(LAS unsigned char* lds, const bf16_t* Qw, int ldq, const bf16_t* Kb, const bf16_t* Vb, int ldk, bf16_t* Ow, int ldo,
;                     int j_first, int ntiles, int jstep, int wj_lo, int wj_hi, int t0) {
;     ...
;                 float pmax = fmaxf(p0[0], p1[0]);
; #pragma unroll
;                 for (int r = 1; r < 15; r += 2) pmax = max3f(pmax, p0[r], p0[r + 1]);
; #pragma unroll
;                 for (int r = 1; r < 15; r += 2) pmax = max3f(pmax, p1[r], p1[r + 1]);
;                 pmax = max3f(pmax, p0[15], p1[15]);
;                 pmax = fmaxf(pmax, xlane32(pmax));
;                 const float pm2 = (MODE == M_BAND) ? pmax : pmax * C2;
;                 float mn = m_reg;
;                 if (!__all(pm2 - m_reg <= 8.f)) {
;                     mn = fmaxf(m_reg, pm2); const float alpha = __builtin_amdgcn_exp2f(m_reg - mn); m_reg = mn; l_reg *= alpha;
;                     if (hi == 0) al_l[r32] = alpha; asm volatile("s_waitcnt lgkmcnt(0)" ::: "memory");
; #pragma unroll
;                     for (int r = 0; r < 16; ++r) { const float af = al_l[crow(r, hi)];
; #pragma unroll
;                         for (int d = 0; d < 4; ++d) o[d][r] *= af; }
;                 }
.LBB11_1656:
	v_add_u32_e32 v184, s4, v175
	s_waitcnt lgkmcnt(0)
	s_barrier
	v_and_b32_e32 v186, 64, v215
	v_add_u32_e32 v186, 64, v186
	s_mov_b32 s4, 0x41000000
	v_add_u32_e32 v185, v184, v176
	ds_read_b128 v[220:223], v185 offset:32768
	v_add_u32_e32 v236, v184, v177
	ds_read_b128 v[224:227], v236 offset:32768
	v_add_u32_e32 v237, v184, v178
	ds_read_b128 v[228:231], v237 offset:32768
	v_add_u32_e32 v238, v184, v179
	ds_read_b128 v[232:235], v238 offset:32768
	s_waitcnt lgkmcnt(3)
	v_mfma_f32_32x32x16_bf16 v[68:83], v[220:223], v[100:103], 0
	v_add_u32_e32 v185, v184, v181
	ds_read_b128 v[220:223], v185 offset:32768
	s_waitcnt lgkmcnt(3)
	v_mfma_f32_32x32x16_bf16 v[68:83], v[224:227], v[104:107], v[68:83]
	v_add_u32_e32 v236, v184, v183
	ds_read_b128 v[224:227], v236 offset:32768
	s_waitcnt lgkmcnt(3)
	v_mfma_f32_32x32x16_bf16 v[68:83], v[228:231], v[108:111], v[68:83]
	v_add_u32_e32 v237, v184, v198
	ds_read_b128 v[228:231], v237 offset:32768
	s_waitcnt lgkmcnt(3)
	v_mfma_f32_32x32x16_bf16 v[68:83], v[232:235], v[112:115], v[68:83]
	v_add_u32_e32 v238, v184, v176
	ds_read_b128 v[232:235], v238 offset:40960
	s_waitcnt lgkmcnt(3)
	v_mfma_f32_32x32x16_bf16 v[68:83], v[220:223], v[116:119], v[68:83]
	v_add_u32_e32 v185, v184, v177
	ds_read_b128 v[220:223], v185 offset:40960
	s_waitcnt lgkmcnt(3)
	v_mfma_f32_32x32x16_bf16 v[68:83], v[224:227], v[120:123], v[68:83]
	v_add_u32_e32 v236, v184, v178
	ds_read_b128 v[224:227], v236 offset:40960
	s_waitcnt lgkmcnt(3)
	v_mfma_f32_32x32x16_bf16 v[68:83], v[228:231], v[124:127], v[68:83]
	v_add_u32_e32 v237, v184, v179
	ds_read_b128 v[228:231], v237 offset:40960
	s_waitcnt lgkmcnt(3)
	v_mfma_f32_32x32x16_bf16 v[84:99], v[232:235], v[100:103], 0
	v_add_u32_e32 v238, v184, v181
	ds_read_b128 v[232:235], v238 offset:40960
	s_waitcnt lgkmcnt(3)
	v_mfma_f32_32x32x16_bf16 v[84:99], v[220:223], v[104:107], v[84:99]
	v_add_u32_e32 v185, v184, v183
	ds_read_b128 v[220:223], v185 offset:40960
	s_waitcnt lgkmcnt(3)
	v_mfma_f32_32x32x16_bf16 v[84:99], v[224:227], v[108:111], v[84:99]
	v_add_u32_e32 v236, v184, v198
	ds_read_b128 v[224:227], v236 offset:40960
	s_waitcnt lgkmcnt(3)
	v_mfma_f32_32x32x16_bf16 v[84:99], v[228:231], v[112:115], v[84:99]
	v_add_u32_e32 v237, v184, v199
	ds_read_b128 v[228:231], v237 offset:40960
	s_waitcnt lgkmcnt(3)
	v_mfma_f32_32x32x16_bf16 v[84:99], v[232:235], v[116:119], v[84:99]
	v_add_u32_e32 v238, v184, v199
	ds_read_b128 v[232:235], v238 offset:32768
	s_waitcnt lgkmcnt(3)
	v_mfma_f32_32x32x16_bf16 v[84:99], v[220:223], v[120:123], v[84:99]
	s_waitcnt lgkmcnt(2)
	v_mfma_f32_32x32x16_bf16 v[84:99], v[224:227], v[124:127], v[84:99]
	s_waitcnt lgkmcnt(1)
	v_mfma_f32_32x32x16_bf16 v[84:99], v[228:231], v[128:131], v[84:99]
	s_waitcnt lgkmcnt(0)
	v_mfma_f32_32x32x16_bf16 v[68:83], v[232:235], v[128:131], v[68:83]
	s_nop 8
	v_max_f32_e32 v184, v84, v84
	s_nop 1
	v_max_f32_e32 v185, v68, v68
	v_max_f32_e32 v184, v185, v184
	v_max3_f32 v184, v184, v69, v70
	v_xor_b32_e32 v185, 32, v215
	v_max3_f32 v184, v184, v71, v72
	v_cmp_lt_i32_e32 vcc, v185, v186
	v_max3_f32 v184, v184, v73, v74
	s_nop 0
	v_max3_f32 v184, v184, v75, v76
	s_nop 0
	v_max3_f32 v184, v184, v77, v78
	v_cndmask_b32_e32 v185, v215, v185, vcc
	v_max3_f32 v184, v184, v79, v80
	v_lshlrev_b32_e32 v204, 2, v185
	v_max3_f32 v184, v184, v81, v82
	s_nop 0
	v_max3_f32 v184, v184, v85, v86
	s_nop 0
	v_max3_f32 v184, v184, v87, v88
	s_nop 0
	v_max3_f32 v184, v184, v89, v90
	s_nop 0
	v_max3_f32 v184, v184, v91, v92
	s_nop 0
	v_max3_f32 v184, v184, v93, v94
	s_nop 0
	v_max3_f32 v184, v184, v95, v96
	s_nop 0
	v_max3_f32 v184, v184, v97, v98
	s_nop 0
	v_max3_f32 v184, v184, v83, v99
	ds_bpermute_b32 v185, v204, v184
	v_max_f32_e32 v184, v184, v184
	s_waitcnt lgkmcnt(0)
	v_max_f32_e32 v185, v185, v185
	v_max_f32_e32 v205, v184, v185
	v_fma_f32 v184, v205, s0, -v206
	v_cmp_ge_f32_e32 vcc, s4, v184
	s_cmp_eq_u64 vcc, exec
	s_cbranch_scc1 .LBB11_1660
	v_mul_f32_e32 v184, 0x3e0293ee, v205
	v_max_f32_e32 v184, v184, v184
	v_max_f32_e32 v185, v206, v206
	v_max_f32_e32 v205, v185, v184
	v_sub_f32_e32 v184, v206, v205
	v_exp_f32_e32 v206, v184
	s_and_saveexec_b64 s[4:5], s[40:41]
	ds_write_b32 v180, v206 offset:128
	s_or_b64 exec, exec, s[4:5]
	s_waitcnt lgkmcnt(0)
	v_add_u32_e32 v184, v167, v162
	ds_read_b128 v[220:223], v184 offset:128
	ds_read_b128 v[224:227], v184 offset:160
	ds_read_b128 v[228:231], v184 offset:192
	ds_read_b128 v[232:235], v184 offset:224
	v_mul_f32_e32 v203, v203, v206
	s_waitcnt lgkmcnt(3)
	v_pk_mul_f32 v[6:7], v[6:7], v[222:223]
	s_waitcnt lgkmcnt(2)
	v_pk_mul_f32 v[8:9], v[8:9], v[224:225]
	s_waitcnt lgkmcnt(1)
	v_pk_mul_f32 v[12:13], v[12:13], v[228:229]
	s_waitcnt lgkmcnt(0)
	v_pk_mul_f32 v[16:17], v[16:17], v[232:233]
	v_pk_mul_f32 v[18:19], v[18:19], v[234:235]
	v_pk_mul_f32 v[14:15], v[14:15], v[230:231]
	v_pk_mul_f32 v[10:11], v[10:11], v[226:227]
	v_pk_mul_f32 v[4:5], v[4:5], v[220:221]
	v_pk_mul_f32 v[64:65], v[64:65], v[232:233]
	v_pk_mul_f32 v[60:61], v[60:61], v[228:229]
	v_pk_mul_f32 v[56:57], v[56:57], v[224:225]
	v_pk_mul_f32 v[66:67], v[66:67], v[234:235]
	v_pk_mul_f32 v[62:63], v[62:63], v[230:231]
	v_pk_mul_f32 v[58:59], v[58:59], v[226:227]
	v_pk_mul_f32 v[54:55], v[54:55], v[222:223]
	v_pk_mul_f32 v[52:53], v[52:53], v[220:221]
	v_pk_mul_f32 v[48:49], v[48:49], v[232:233]
	v_pk_mul_f32 v[44:45], v[44:45], v[228:229]
	v_pk_mul_f32 v[40:41], v[40:41], v[224:225]
	v_pk_mul_f32 v[50:51], v[50:51], v[234:235]
	v_pk_mul_f32 v[46:47], v[46:47], v[230:231]
	v_pk_mul_f32 v[42:43], v[42:43], v[226:227]
	v_pk_mul_f32 v[38:39], v[38:39], v[222:223]
	v_pk_mul_f32 v[36:37], v[36:37], v[220:221]
	v_pk_mul_f32 v[32:33], v[32:33], v[232:233]
	v_pk_mul_f32 v[28:29], v[28:29], v[228:229]
	v_pk_mul_f32 v[24:25], v[24:25], v[224:225]
	v_pk_mul_f32 v[34:35], v[34:35], v[234:235]
	v_pk_mul_f32 v[30:31], v[30:31], v[230:231]
	v_pk_mul_f32 v[26:27], v[26:27], v[226:227]
	v_pk_mul_f32 v[22:23], v[22:23], v[222:223]
	v_pk_mul_f32 v[20:21], v[20:21], v[220:221]
	s_branch .LBB11_1661
